# baseline (speedup 1.0000x reference)
; #define KSWZ(row, colB) ((row) * 256 + ((colB) ^ (KSWZF(row) << 4)))
; #define LDS_AS3(ptr) ((__attribute__((address_space(3))) unsigned*)(ptr))
; __device__ void compress_item(const Params& p, int which, int g, int ct, char* smem) {
;   int tid = threadIdx.x; asm volatile("" : "+v"(tid) :: "memory");
;   const int wid = tid >> 6, lane = tid & 63, r32 = lane & 31, hi = lane >> 5, mb = wid & 1, nb = wid >> 1;
;   const int widu = __builtin_amdgcn_readfirstlane(wid);
;   const bf16* src = p.P + (which ? C_VC : C_KC) + g * 128;
;   const bf16* w1T = which ? p.w1vT : p.w1kT; const bf16* w2T = which ? p.w2vT : p.w2kT; const float* b1 = which ? p.bias1v : p.bias1k;
;   bf16* dst = (which ? p.vcmp : p.kcmp) + (long)g * NCP * 128;
;   auto issue = [&](int r, int buf) {
; #pragma unroll
;     for (int i = 0; i < 2; ++i) { const int s_ = tid + 512 * i, row = s_ >> 4, ch = (s_ & 15) ^ KSWZF(row);
;       int tr = 16 * (ct * 64 + row) + r; if (tr > T - 1) tr = T - 1;
;       const unsigned offb = (unsigned)(tr * LDP + ch * 8) * 2u;
;       __builtin_amdgcn_global_load_lds((const unsigned*)((const char*)src + offb), LDS_AS3(smem + buf * 16384 + (widu * 64 + 512 * i) * 16), 16, 0, 0); }
; #pragma unroll
;     for (int i = 0; i < 4; ++i) { const int s_ = tid + 512 * i, row = s_ >> 4, ch = (s_ & 15) ^ KSWZF(row);
;       const unsigned offb = (unsigned)(row * DM + r * 128 + ch * 8) * 2u;
;       __builtin_amdgcn_global_load_lds((const unsigned*)((const char*)w1T + offb), LDS_AS3(smem + 32768 + buf * 32768 + (widu * 64 + 512 * i) * 16), 16, 0, 0); }
;   };
;   f32x16 acc = {};
;   __syncthreads();
;   issue(0, 0);
;     ...
;     for (int d0 = 0; d0 < 8; ++d0) { const int cb = (d0 * 16 + hi * 8) * 2;
;       bf16x8 a = *reinterpret_cast<const bf16x8*>(A_l + KSWZ(32 * mb + r32, cb));
;       bf16x8 b = *reinterpret_cast<const bf16x8*>(B_l + KSWZ(32 * nb + r32, cb));
.LBB0_217:
	s_and_b64 vcc, exec, s[2:3]
	s_cbranch_vccz .LBB0_202
	s_bfe_u32 s2, s0, 0x20004
	s_and_b32 s1, s0, 15
	s_cmp_lt_u32 s0, 64
	v_readlane_b32 s60, v252, 18
	s_cselect_b64 s[12:13], -1, 0
	v_readlane_b32 s61, v252, 19
	v_readlane_b32 s62, v252, 20
	v_readlane_b32 s63, v252, 21
	v_readlane_b32 s64, v252, 22
	v_readlane_b32 s65, v252, 23
	v_readlane_b32 s66, v252, 24
	v_readlane_b32 s67, v252, 25
	v_readlane_b32 s68, v252, 26
	v_readlane_b32 s69, v252, 27
	v_readlane_b32 s70, v252, 28
	v_readlane_b32 s71, v252, 29
	s_and_b64 s[14:15], s[12:13], exec
	v_readlane_b32 s72, v252, 30
	v_readlane_b32 s73, v252, 31
	v_readlane_b32 s74, v252, 32
	v_readlane_b32 s75, v252, 33
	s_mov_b64 s[60:61], s[64:65]
	v_mov_b32_e32 v19, v1
	s_cselect_b32 s0, 0x1000, s22
	s_mov_b64 s[62:63], s[66:67]
	s_cselect_b32 s14, s60, s62
	v_lshrrev_b32_e32 v3, 5, v19
	s_cselect_b32 s15, s61, s63
	s_add_u32 s0, s46, s0
	v_and_b32_e32 v6, -16, v19
	v_ashrrev_i32_e32 v2, 6, v19
	s_addc_u32 s16, s47, 0
	s_lshl_b32 s42, s2, 8
	v_and_b32_e32 v4, 15, v19
	v_bfe_u32 v5, v19, 4, 3
	v_and_b32_e32 v3, 8, v3
	v_lshl_add_u32 v20, s1, 10, v6
	v_readfirstlane_b32 s3, v2
	s_add_u32 s42, s0, s42
	v_bitop3_b32 v5, v5, v4, v3 bitop3:0x36
	v_min_i32_e32 v6, 0x3fff, v20
	s_addc_u32 s43, s16, 0
	v_lshlrev_b32_e32 v21, 4, v5
	v_mul_lo_u32 v5, v6, s52
	s_lshl_b32 s0, s3, 10
	v_or_b32_e32 v5, v21, v5
	s_mov_b32 m0, s0
	s_barrier
	global_load_lds_dwordx4 v5, s[42:43]
	v_add_u32_e32 v5, 0x200, v20
	v_min_i32_e32 v5, 0x3fff, v5
	v_mul_lo_u32 v5, v5, s52
	v_ashrrev_i32_e32 v18, 4, v19
	v_or_b32_e32 v5, v5, v21
	s_add_i32 m0, s0, 0x2000
	v_and_b32_e32 v25, 7, v18
	global_load_lds_dwordx4 v5, s[42:43]
	v_bitop3_b32 v5, v25, v4, v3 bitop3:0x36
	v_lshlrev_b32_e32 v6, 13, v18
	v_lshl_or_b32 v5, v5, 4, v6
	v_add_u32_e32 v6, 0x200, v19
	v_ashrrev_i32_e32 v6, 4, v6
	v_and_b32_e32 v7, 7, v6
	v_bitop3_b32 v7, v7, v4, v3 bitop3:0x36
	v_lshlrev_b32_e32 v6, 13, v6
	v_lshl_or_b32 v6, v7, 4, v6
	v_add_u32_e32 v7, 0x400, v19
	v_ashrrev_i32_e32 v7, 4, v7
	v_and_b32_e32 v8, 7, v7
	v_bitop3_b32 v8, v8, v4, v3 bitop3:0x36
	v_lshlrev_b32_e32 v7, 13, v7
	v_lshl_or_b32 v7, v8, 4, v7
	v_add_u32_e32 v8, 0x600, v19
	s_add_i32 m0, s0, 0x8000
	v_ashrrev_i32_e32 v8, 4, v8
	global_load_lds_dwordx4 v5, s[14:15]
	s_add_i32 m0, s0, 0xa000
	v_and_b32_e32 v9, 7, v8
	global_load_lds_dwordx4 v6, s[14:15]
	s_add_i32 m0, s0, 0xc000
	v_bitop3_b32 v3, v9, v4, v3 bitop3:0x36
	v_lshlrev_b32_e32 v4, 13, v8
	global_load_lds_dwordx4 v7, s[14:15]
	v_lshl_or_b32 v3, v3, 4, v4
	s_add_i32 m0, s0, 0xe000
	v_and_b32_e32 v9, 7, v19
	global_load_lds_dwordx4 v3, s[14:15]
	v_mov_b32_e32 v250, v20
	v_add_u32_e32 v251, 1, v250
	v_min_i32_e32 v251, 0x3fff, v251
	v_add_u32_e32 v250, 0x201, v250
	v_mul_lo_u32 v251, v251, s52
	v_min_i32_e32 v250, 0x3fff, v250
	v_or_b32_e32 v251, v251, v21
	v_mul_lo_u32 v250, v250, s52
	global_load_dword v248, v251, s[42:43]
	v_or_b32_e32 v250, v250, v21
	global_load_dword v249, v250, s[42:43]
	v_lshrrev_b32_e32 v10, 1, v19
	v_and_b32_e32 v45, 31, v19
	v_bfe_u32 v44, v19, 5, 1
	v_and_b32_e32 v24, 1, v2
	v_and_or_b32 v9, v10, 8, v9
	v_ashrrev_i32_e32 v46, 7, v19
	v_lshlrev_b32_e32 v2, 4, v44
	v_lshlrev_b32_e32 v43, 13, v24
	v_lshlrev_b32_e32 v4, 8, v45
	v_lshlrev_b32_e32 v9, 4, v9
	v_or_b32_e32 v8, v43, v4
	v_lshl_or_b32 v4, v46, 13, v4
	v_xor_b32_e32 v10, v9, v2
	v_or_b32_e32 v38, v10, v8
	v_or_b32_e32 v39, v10, v4
	v_bitop3_b32 v10, v2, v9, 32 bitop3:0x36
	v_or_b32_e32 v40, v10, v8
	v_or_b32_e32 v41, v10, v4
	v_bitop3_b32 v10, v2, v9, 64 bitop3:0x36
	v_or_b32_e32 v36, v10, v8
	v_or_b32_e32 v37, v10, v4
	v_bitop3_b32 v10, v2, v9, s53 bitop3:0x36
	v_or_b32_e32 v34, v10, v8
	v_or_b32_e32 v35, v10, v4
	v_bitop3_b32 v10, v2, v9, s54 bitop3:0x36
	v_or_b32_e32 v32, v10, v8
	v_or_b32_e32 v33, v10, v4
	v_bitop3_b32 v10, v2, v9, s55 bitop3:0x36
	v_or_b32_e32 v30, v10, v8
	v_or_b32_e32 v31, v10, v4
	v_bitop3_b32 v10, v2, v9, s4 bitop3:0x36
	v_bitop3_b32 v2, v2, v9, s56 bitop3:0x36
	v_or_b32_e32 v27, v2, v8
	v_or_b32_e32 v26, v2, v4
	v_mov_b32_e32 v2, 0
	s_mov_b32 s3, 0
	v_or_b32_e32 v28, v10, v8
	v_or_b32_e32 v29, v10, v4
	v_or_b32_e32 v22, 0x100, v3
	v_or_b32_e32 v23, 0x100, v7
	v_or_b32_e32 v42, 0x100, v6
	v_or_b32_e32 v47, 0x100, v5
	s_mov_b32 s16, 0
	v_mov_b32_e32 v3, v2
	v_mov_b32_e32 v4, v2
	v_mov_b32_e32 v5, v2
	v_mov_b32_e32 v6, v2
	v_mov_b32_e32 v7, v2
	v_mov_b32_e32 v8, v2
	v_mov_b32_e32 v9, v2
	v_mov_b32_e32 v10, v2
	v_mov_b32_e32 v11, v2
	v_mov_b32_e32 v12, v2
	v_mov_b32_e32 v13, v2
	v_mov_b32_e32 v14, v2
	v_mov_b32_e32 v15, v2
	v_mov_b32_e32 v16, v2
	v_mov_b32_e32 v17, v2
	s_mov_b64 s[64:65], s[68:69]
	s_mov_b64 s[66:67], s[70:71]
	s_mov_b64 s[68:69], s[72:73]
	s_mov_b64 s[70:71], s[74:75]
	s_branch .LBB0_220

; #define LDS_AS3(ptr) ((__attribute__((address_space(3))) unsigned*)(ptr))
; __device__ void compress_item(const Params& p, int which, int g, int ct, char* smem) {
;     ...
;   auto issue = [&](int r, int buf) {
; #pragma unroll
;     for (int i = 0; i < 2; ++i) { const int s_ = tid + 512 * i, row = s_ >> 4, ch = (s_ & 15) ^ KSWZF(row);
;       int tr = 16 * (ct * 64 + row) + r; if (tr > T - 1) tr = T - 1;
;       const unsigned offb = (unsigned)(tr * LDP + ch * 8) * 2u;
;       __builtin_amdgcn_global_load_lds((const unsigned*)((const char*)src + offb), LDS_AS3(smem + buf * 16384 + (widu * 64 + 512 * i) * 16), 16, 0, 0); }
; #pragma unroll
;     for (int i = 0; i < 4; ++i) { const int s_ = tid + 512 * i, row = s_ >> 4, ch = (s_ & 15) ^ KSWZF(row);
;       const unsigned offb = (unsigned)(row * DM + r * 128 + ch * 8) * 2u;
;       __builtin_amdgcn_global_load_lds((const unsigned*)((const char*)w1T + offb), LDS_AS3(smem + 32768 + buf * 32768 + (widu * 64 + 512 * i) * 16), 16, 0, 0); }
;   };
;     ...
;   for (int r = 0; r < 32; ++r) {
;     const int buf = r & 1;
;     asm volatile("s_waitcnt vmcnt(0)" ::: "memory");
;     __syncthreads();
;     if (r + 1 < 32) issue(r + 1, buf ^ 1);
.LBB0_220:
	s_waitcnt vmcnt(2)
	s_and_b32 s58, s16, 1
	s_cmpk_eq_i32 s3, 0x1f00
	s_waitcnt vmcnt(2) lgkmcnt(0)
	s_barrier
	s_cbranch_scc1 .LBB0_219
	v_add_u32_e32 v48, s16, v20
	s_xor_b32 s59, s58, 1
	v_add_u32_e32 v49, 1, v48
	s_lshl_b32 s59, s59, 14
	v_min_i32_e32 v49, 0x3fff, v49
	v_add_u32_e32 v48, 0x201, v48
	v_mul_lo_u32 v49, v49, s52
	s_add_i32 s60, s59, s0
	v_min_i32_e32 v48, 0x3fff, v48
	v_or_b32_e32 v49, v49, v21
	s_mov_b32 m0, s60
	v_mul_lo_u32 v48, v48, s52
	global_load_lds_dwordx4 v49, s[42:43]
	v_or_b32_e32 v48, v48, v21
	s_add_i32 m0, s60, 0x2000
	s_add_i32 s59, s60, s59
	global_load_lds_dwordx4 v48, s[42:43]
	v_add_u32_e32 v48, s3, v47
	s_add_i32 m0, s59, 0x8000
	s_nop 0
	global_load_lds_dwordx4 v48, s[14:15]
	v_add_u32_e32 v48, s3, v42
	s_add_i32 m0, s59, 0xa000
	s_nop 0
	global_load_lds_dwordx4 v48, s[14:15]
	v_add_u32_e32 v48, s3, v23
	s_add_i32 m0, s59, 0xc000
	s_nop 0
	global_load_lds_dwordx4 v48, s[14:15]
	v_add_u32_e32 v48, s3, v22
	s_add_i32 m0, s59, 0xe000
	s_nop 0
	global_load_lds_dwordx4 v48, s[14:15]
	v_add_u32_e32 v250, s16, v20
	v_add_u32_e32 v251, 2, v250
	v_min_i32_e32 v251, 0x3fff, v251
	v_add_u32_e32 v250, 0x202, v250
	v_mul_lo_u32 v251, v251, s52
	v_min_i32_e32 v250, 0x3fff, v250
	v_or_b32_e32 v251, v251, v21
	v_mul_lo_u32 v250, v250, s52
	global_load_dword v248, v251, s[42:43]
	v_or_b32_e32 v250, v250, v21
	global_load_dword v249, v250, s[42:43]
	s_branch .LBB0_219
